# residual-update epilogue: 32 more dead lane-base instructions removed
# baseline (speedup 1.0000x reference)
;     DI void operator()(const f32x4 (&acc)[2][2][4][2], const Unit& u, int wr, int wc, int fr, int fq) const {
;     ...
;                         ss += (x0[0] * x0[0] + x0[1] * x0[1]) + (x0[2] * x0[2] + x0[3] * x0[3]) + (x1[0] * x1[0] + x1[1] * x1[1]) + (x1[2] * x1[2] + x1[3] * x1[3]);
;                     }
;                     if (rss) { ss += __shfl_xor(ss, 16); ss += __shfl_xor(ss, 32); if (fq == 0) rss[(size_t)row * 16 + u.pn * 4 + wc] = ss; }
.LBB0_465:
	s_lshl_b32 s82, s95, 2
	s_nop 0
	v_cndmask_b32_e64 v202, 0, 1, s[52:53]
	v_cmp_ne_u32_e64 s[12:13], 1, v202
	s_andn2_b64 vcc, exec, s[52:53]
	s_ashr_i32 s83, s82, 31
	s_cbranch_vccnz .LBB0_469
	v_mul_f32_e32 v195, v195, v195
	v_fmac_f32_e32 v195, v194, v194
	v_mul_f32_e32 v194, v197, v197
	v_fmac_f32_e32 v194, v196, v196
	v_mul_f32_e32 v191, v191, v191
	v_add_f32_e32 v194, v195, v194
	v_fmac_f32_e32 v191, v190, v190
	v_mul_f32_e32 v187, v187, v187
	v_add_f32_e32 v190, v191, v194
	v_mul_f32_e32 v191, v193, v193
	v_fmac_f32_e32 v187, v186, v186
	v_mul_f32_e32 v186, v189, v189
	v_fmac_f32_e32 v191, v192, v192
	v_mul_f32_e32 v192, v199, v199
	v_fmac_f32_e32 v186, v188, v188
	v_add_f32_e32 v190, v191, v190
	v_mul_f32_e32 v191, v201, v201
	v_fmac_f32_e32 v192, v198, v198
	v_add_f32_e32 v186, v187, v186
	v_fmac_f32_e32 v191, v200, v200
	v_add_f32_e32 v186, v192, v186
	v_add_f32_e32 v186, v191, v186
	v_add_f32_e32 v186, v190, v186
	v_mov_b32_e32 v187, v186
	s_nop 1
	v_permlane16_swap_b32_e32 v187, v186
	s_waitcnt lgkmcnt(0)
	v_add_f32_e32 v186, v186, v187
	s_nop 1
	v_mov_b32_e32 v187, v186
	s_nop 1
	v_permlane32_swap_b32_e32 v187, v186
	s_and_saveexec_b64 vcc, s[4:5]
	s_cbranch_execz .LBB0_468
	v_readlane_b32 s26, v255, 5
	s_waitcnt lgkmcnt(0)
	v_add_f32_e32 v188, v186, v187
	v_lshlrev_b64 v[186:187], 6, v[234:235]
	v_readlane_b32 s27, v255, 6
	s_lshl_b32 s46, s43, 2
	s_nop 0
	v_lshl_add_u64 v[186:187], s[26:27], 0, v[186:187]
	v_lshl_add_u64 v[186:187], s[82:83], 2, v[186:187]
	v_lshl_add_u64 v[186:187], v[186:187], 0, s[46:47]
	global_store_dword v[186:187], v188, off

;     DI void operator()(const f32x4 (&acc)[2][2][4][2], const Unit& u, int wr, int wc, int fr, int fq) const {
;     ...
;                         ss += (x0[0] * x0[0] + x0[1] * x0[1]) + (x0[2] * x0[2] + x0[3] * x0[3]) + (x1[0] * x1[0] + x1[1] * x1[1]) + (x1[2] * x1[2] + x1[3] * x1[3]);
;                     }
;                     if (rss) { ss += __shfl_xor(ss, 16); ss += __shfl_xor(ss, 32); if (fq == 0) rss[(size_t)row * 16 + u.pn * 4 + wc] = ss; }
.LBB0_477:
	s_and_b64 vcc, exec, s[12:13]
	s_cbranch_vccnz .LBB0_481
	v_mul_f32_e32 v183, v183, v183
	v_fmac_f32_e32 v183, v182, v182
	v_mul_f32_e32 v182, v185, v185
	v_fmac_f32_e32 v182, v184, v184
	v_add_f32_e32 v182, v183, v182
	v_mul_f32_e32 v183, v187, v187
	v_fmac_f32_e32 v183, v186, v186
	v_mul_f32_e32 v179, v179, v179
	v_add_f32_e32 v182, v183, v182
	v_mul_f32_e32 v183, v189, v189
	v_fmac_f32_e32 v179, v178, v178
	v_mul_f32_e32 v178, v181, v181
	v_fmac_f32_e32 v183, v188, v188
	v_mul_f32_e32 v184, v191, v191
	v_fmac_f32_e32 v178, v180, v180
	v_add_f32_e32 v182, v183, v182
	v_mul_f32_e32 v183, v193, v193
	v_fmac_f32_e32 v184, v190, v190
	v_add_f32_e32 v178, v179, v178
	v_fmac_f32_e32 v183, v192, v192
	v_add_f32_e32 v178, v184, v178
	v_add_f32_e32 v178, v183, v178
	v_add_f32_e32 v178, v182, v178
	v_mov_b32_e32 v179, v178
	s_nop 1
	v_permlane16_swap_b32_e32 v179, v178
	s_waitcnt lgkmcnt(0)
	v_add_f32_e32 v178, v178, v179
	s_nop 1
	v_mov_b32_e32 v179, v178
	s_nop 1
	v_permlane32_swap_b32_e32 v179, v178
	s_and_saveexec_b64 vcc, s[4:5]
	s_cbranch_execz .LBB0_480
	v_readlane_b32 s26, v255, 5
	s_waitcnt lgkmcnt(0)
	v_add_f32_e32 v180, v178, v179
	v_lshlrev_b64 v[178:179], 6, v[232:233]
	v_readlane_b32 s27, v255, 6
	s_lshl_b32 s46, s43, 2
	s_nop 0
	v_lshl_add_u64 v[178:179], s[26:27], 0, v[178:179]
	v_lshl_add_u64 v[178:179], s[82:83], 2, v[178:179]
	v_lshl_add_u64 v[178:179], v[178:179], 0, s[46:47]
	global_store_dword v[178:179], v180, off

;     DI void operator()(const f32x4 (&acc)[2][2][4][2], const Unit& u, int wr, int wc, int fr, int fq) const {
;     ...
;                         ss += (x0[0] * x0[0] + x0[1] * x0[1]) + (x0[2] * x0[2] + x0[3] * x0[3]) + (x1[0] * x1[0] + x1[1] * x1[1]) + (x1[2] * x1[2] + x1[3] * x1[3]);
;                     }
;                     if (rss) { ss += __shfl_xor(ss, 16); ss += __shfl_xor(ss, 32); if (fq == 0) rss[(size_t)row * 16 + u.pn * 4 + wc] = ss; }
.LBB0_489:
	s_and_b64 vcc, exec, s[12:13]
	s_cbranch_vccnz .LBB0_493
	v_mul_f32_e32 v175, v175, v175
	v_fmac_f32_e32 v175, v174, v174
	v_mul_f32_e32 v174, v177, v177
	v_fmac_f32_e32 v174, v176, v176
	v_add_f32_e32 v174, v175, v174
	v_mul_f32_e32 v175, v179, v179
	v_fmac_f32_e32 v175, v178, v178
	v_mul_f32_e32 v171, v171, v171
	v_add_f32_e32 v174, v175, v174
	v_mul_f32_e32 v175, v181, v181
	v_fmac_f32_e32 v171, v170, v170
	v_mul_f32_e32 v170, v173, v173
	v_fmac_f32_e32 v175, v180, v180
	v_mul_f32_e32 v176, v183, v183
	v_fmac_f32_e32 v170, v172, v172
	v_add_f32_e32 v174, v175, v174
	v_mul_f32_e32 v175, v185, v185
	v_fmac_f32_e32 v176, v182, v182
	v_add_f32_e32 v170, v171, v170
	v_fmac_f32_e32 v175, v184, v184
	v_add_f32_e32 v170, v176, v170
	v_add_f32_e32 v170, v175, v170
	v_add_f32_e32 v170, v174, v170
	v_mov_b32_e32 v171, v170
	s_nop 1
	v_permlane16_swap_b32_e32 v171, v170
	s_waitcnt lgkmcnt(0)
	v_add_f32_e32 v170, v170, v171
	s_nop 1
	v_mov_b32_e32 v171, v170
	s_nop 1
	v_permlane32_swap_b32_e32 v171, v170
	s_and_saveexec_b64 vcc, s[4:5]
	s_cbranch_execz .LBB0_492
	v_readlane_b32 s26, v255, 5
	s_waitcnt lgkmcnt(0)
	v_add_f32_e32 v172, v170, v171
	v_lshlrev_b64 v[170:171], 6, v[230:231]
	v_readlane_b32 s27, v255, 6
	s_lshl_b32 s46, s43, 2
	s_nop 0
	v_lshl_add_u64 v[170:171], s[26:27], 0, v[170:171]
	v_lshl_add_u64 v[170:171], s[82:83], 2, v[170:171]
	v_lshl_add_u64 v[170:171], v[170:171], 0, s[46:47]
	global_store_dword v[170:171], v172, off

;     DI void operator()(const f32x4 (&acc)[2][2][4][2], const Unit& u, int wr, int wc, int fr, int fq) const {
;     ...
;                         ss += (x0[0] * x0[0] + x0[1] * x0[1]) + (x0[2] * x0[2] + x0[3] * x0[3]) + (x1[0] * x1[0] + x1[1] * x1[1]) + (x1[2] * x1[2] + x1[3] * x1[3]);
;                     }
;                     if (rss) { ss += __shfl_xor(ss, 16); ss += __shfl_xor(ss, 32); if (fq == 0) rss[(size_t)row * 16 + u.pn * 4 + wc] = ss; }
.LBB0_501:
	s_and_b64 vcc, exec, s[12:13]
	s_cbranch_vccnz .LBB0_505
	v_mul_f32_e32 v167, v167, v167
	v_fmac_f32_e32 v167, v166, v166
	v_mul_f32_e32 v166, v169, v169
	v_fmac_f32_e32 v166, v168, v168
	v_add_f32_e32 v166, v167, v166
	v_mul_f32_e32 v167, v171, v171
	v_fmac_f32_e32 v167, v170, v170
	v_mul_f32_e32 v163, v163, v163
	v_add_f32_e32 v166, v167, v166
	v_mul_f32_e32 v167, v173, v173
	v_fmac_f32_e32 v163, v162, v162
	v_mul_f32_e32 v162, v165, v165
	v_fmac_f32_e32 v167, v172, v172
	v_mul_f32_e32 v168, v175, v175
	v_fmac_f32_e32 v162, v164, v164
	v_add_f32_e32 v166, v167, v166
	v_mul_f32_e32 v167, v177, v177
	v_fmac_f32_e32 v168, v174, v174
	v_add_f32_e32 v162, v163, v162
	v_fmac_f32_e32 v167, v176, v176
	v_add_f32_e32 v162, v168, v162
	v_add_f32_e32 v162, v167, v162
	v_add_f32_e32 v162, v166, v162
	v_mov_b32_e32 v163, v162
	s_nop 1
	v_permlane16_swap_b32_e32 v163, v162
	s_waitcnt lgkmcnt(0)
	v_add_f32_e32 v162, v162, v163
	s_nop 1
	v_mov_b32_e32 v163, v162
	s_nop 1
	v_permlane32_swap_b32_e32 v163, v162
	s_and_saveexec_b64 vcc, s[4:5]
	s_cbranch_execz .LBB0_504
	v_readlane_b32 s26, v255, 5
	s_waitcnt lgkmcnt(0)
	v_add_f32_e32 v164, v162, v163
	v_lshlrev_b64 v[162:163], 6, v[228:229]
	v_readlane_b32 s27, v255, 6
	s_lshl_b32 s46, s43, 2
	s_nop 0
	v_lshl_add_u64 v[162:163], s[26:27], 0, v[162:163]
	v_lshl_add_u64 v[162:163], s[82:83], 2, v[162:163]
	v_lshl_add_u64 v[162:163], v[162:163], 0, s[46:47]
	global_store_dword v[162:163], v164, off

;     DI void operator()(const f32x4 (&acc)[2][2][4][2], const Unit& u, int wr, int wc, int fr, int fq) const {
;     ...
;                         ss += (x0[0] * x0[0] + x0[1] * x0[1]) + (x0[2] * x0[2] + x0[3] * x0[3]) + (x1[0] * x1[0] + x1[1] * x1[1]) + (x1[2] * x1[2] + x1[3] * x1[3]);
;                     }
;                     if (rss) { ss += __shfl_xor(ss, 16); ss += __shfl_xor(ss, 32); if (fq == 0) rss[(size_t)row * 16 + u.pn * 4 + wc] = ss; }
.LBB0_513:
	s_and_b64 vcc, exec, s[12:13]
	s_cbranch_vccnz .LBB0_517
	v_mul_f32_e32 v159, v159, v159
	v_fmac_f32_e32 v159, v158, v158
	v_mul_f32_e32 v158, v161, v161
	v_fmac_f32_e32 v158, v160, v160
	v_add_f32_e32 v158, v159, v158
	v_mul_f32_e32 v159, v163, v163
	v_fmac_f32_e32 v159, v162, v162
	v_mul_f32_e32 v155, v155, v155
	v_add_f32_e32 v158, v159, v158
	v_mul_f32_e32 v159, v165, v165
	v_fmac_f32_e32 v155, v154, v154
	v_mul_f32_e32 v154, v157, v157
	v_fmac_f32_e32 v159, v164, v164
	v_mul_f32_e32 v160, v167, v167
	v_fmac_f32_e32 v154, v156, v156
	v_add_f32_e32 v158, v159, v158
	v_mul_f32_e32 v159, v169, v169
	v_fmac_f32_e32 v160, v166, v166
	v_add_f32_e32 v154, v155, v154
	v_fmac_f32_e32 v159, v168, v168
	v_add_f32_e32 v154, v160, v154
	v_add_f32_e32 v154, v159, v154
	v_add_f32_e32 v154, v158, v154
	v_mov_b32_e32 v155, v154
	s_nop 1
	v_permlane16_swap_b32_e32 v155, v154
	s_waitcnt lgkmcnt(0)
	v_add_f32_e32 v154, v154, v155
	s_nop 1
	v_mov_b32_e32 v155, v154
	s_nop 1
	v_permlane32_swap_b32_e32 v155, v154
	s_and_saveexec_b64 vcc, s[4:5]
	s_cbranch_execz .LBB0_516
	v_readlane_b32 s26, v255, 5
	s_waitcnt lgkmcnt(0)
	v_add_f32_e32 v156, v154, v155
	v_lshlrev_b64 v[154:155], 6, v[226:227]
	v_readlane_b32 s27, v255, 6
	s_lshl_b32 s46, s43, 2
	s_nop 0
	v_lshl_add_u64 v[154:155], s[26:27], 0, v[154:155]
	v_lshl_add_u64 v[154:155], s[82:83], 2, v[154:155]
	v_lshl_add_u64 v[154:155], v[154:155], 0, s[46:47]
	global_store_dword v[154:155], v156, off

;     DI void operator()(const f32x4 (&acc)[2][2][4][2], const Unit& u, int wr, int wc, int fr, int fq) const {
;     ...
;                         ss += (x0[0] * x0[0] + x0[1] * x0[1]) + (x0[2] * x0[2] + x0[3] * x0[3]) + (x1[0] * x1[0] + x1[1] * x1[1]) + (x1[2] * x1[2] + x1[3] * x1[3]);
;                     }
;                     if (rss) { ss += __shfl_xor(ss, 16); ss += __shfl_xor(ss, 32); if (fq == 0) rss[(size_t)row * 16 + u.pn * 4 + wc] = ss; }
.LBB0_525:
	s_and_b64 vcc, exec, s[12:13]
	s_cbranch_vccnz .LBB0_529
	v_mul_f32_e32 v151, v151, v151
	v_fmac_f32_e32 v151, v150, v150
	v_mul_f32_e32 v150, v153, v153
	v_fmac_f32_e32 v150, v152, v152
	v_add_f32_e32 v150, v151, v150
	v_mul_f32_e32 v151, v155, v155
	v_fmac_f32_e32 v151, v154, v154
	v_mul_f32_e32 v147, v147, v147
	v_add_f32_e32 v150, v151, v150
	v_mul_f32_e32 v151, v157, v157
	v_fmac_f32_e32 v147, v146, v146
	v_mul_f32_e32 v146, v149, v149
	v_fmac_f32_e32 v151, v156, v156
	v_mul_f32_e32 v152, v159, v159
	v_fmac_f32_e32 v146, v148, v148
	v_add_f32_e32 v150, v151, v150
	v_mul_f32_e32 v151, v161, v161
	v_fmac_f32_e32 v152, v158, v158
	v_add_f32_e32 v146, v147, v146
	v_fmac_f32_e32 v151, v160, v160
	v_add_f32_e32 v146, v152, v146
	v_add_f32_e32 v146, v151, v146
	v_add_f32_e32 v146, v150, v146
	v_mov_b32_e32 v147, v146
	s_nop 1
	v_permlane16_swap_b32_e32 v147, v146
	s_waitcnt lgkmcnt(0)
	v_add_f32_e32 v146, v146, v147
	s_nop 1
	v_mov_b32_e32 v147, v146
	s_nop 1
	v_permlane32_swap_b32_e32 v147, v146
	s_and_saveexec_b64 vcc, s[4:5]
	s_cbranch_execz .LBB0_528
	v_readlane_b32 s26, v255, 5
	s_waitcnt lgkmcnt(0)
	v_add_f32_e32 v148, v146, v147
	v_lshlrev_b64 v[146:147], 6, v[224:225]
	v_readlane_b32 s27, v255, 6
	s_lshl_b32 s46, s43, 2
	s_nop 0
	v_lshl_add_u64 v[146:147], s[26:27], 0, v[146:147]
	v_lshl_add_u64 v[146:147], s[82:83], 2, v[146:147]
	v_lshl_add_u64 v[146:147], v[146:147], 0, s[46:47]
	global_store_dword v[146:147], v148, off

;     DI void operator()(const f32x4 (&acc)[2][2][4][2], const Unit& u, int wr, int wc, int fr, int fq) const {
;     ...
;                         ss += (x0[0] * x0[0] + x0[1] * x0[1]) + (x0[2] * x0[2] + x0[3] * x0[3]) + (x1[0] * x1[0] + x1[1] * x1[1]) + (x1[2] * x1[2] + x1[3] * x1[3]);
;                     }
;                     if (rss) { ss += __shfl_xor(ss, 16); ss += __shfl_xor(ss, 32); if (fq == 0) rss[(size_t)row * 16 + u.pn * 4 + wc] = ss; }
.LBB0_537:
	s_and_b64 vcc, exec, s[12:13]
	s_cbranch_vccnz .LBB0_541
	v_mul_f32_e32 v143, v143, v143
	v_fmac_f32_e32 v143, v142, v142
	v_mul_f32_e32 v142, v145, v145
	v_fmac_f32_e32 v142, v144, v144
	v_add_f32_e32 v142, v143, v142
	v_mul_f32_e32 v143, v147, v147
	v_fmac_f32_e32 v143, v146, v146
	v_mul_f32_e32 v139, v139, v139
	v_add_f32_e32 v142, v143, v142
	v_mul_f32_e32 v143, v149, v149
	v_fmac_f32_e32 v139, v138, v138
	v_mul_f32_e32 v138, v141, v141
	v_fmac_f32_e32 v143, v148, v148
	v_mul_f32_e32 v144, v151, v151
	v_fmac_f32_e32 v138, v140, v140
	v_add_f32_e32 v142, v143, v142
	v_mul_f32_e32 v143, v153, v153
	v_fmac_f32_e32 v144, v150, v150
	v_add_f32_e32 v138, v139, v138
	v_fmac_f32_e32 v143, v152, v152
	v_add_f32_e32 v138, v144, v138
	v_add_f32_e32 v138, v143, v138
	v_add_f32_e32 v138, v142, v138
	v_mov_b32_e32 v139, v138
	s_nop 1
	v_permlane16_swap_b32_e32 v139, v138
	s_waitcnt lgkmcnt(0)
	v_add_f32_e32 v138, v138, v139
	s_nop 1
	v_mov_b32_e32 v139, v138
	s_nop 1
	v_permlane32_swap_b32_e32 v139, v138
	s_and_saveexec_b64 vcc, s[4:5]
	s_cbranch_execz .LBB0_540
	v_readlane_b32 s26, v255, 5
	s_waitcnt lgkmcnt(0)
	v_add_f32_e32 v140, v138, v139
	v_lshlrev_b64 v[138:139], 6, v[222:223]
	v_readlane_b32 s27, v255, 6
	s_lshl_b32 s46, s43, 2
	s_nop 0
	v_lshl_add_u64 v[138:139], s[26:27], 0, v[138:139]
	v_lshl_add_u64 v[138:139], s[82:83], 2, v[138:139]
	v_lshl_add_u64 v[138:139], v[138:139], 0, s[46:47]
	global_store_dword v[138:139], v140, off

;     DI void operator()(const f32x4 (&acc)[2][2][4][2], const Unit& u, int wr, int wc, int fr, int fq) const {
;     ...
;                         ss += (x0[0] * x0[0] + x0[1] * x0[1]) + (x0[2] * x0[2] + x0[3] * x0[3]) + (x1[0] * x1[0] + x1[1] * x1[1]) + (x1[2] * x1[2] + x1[3] * x1[3]);
;                     }
;                     if (rss) { ss += __shfl_xor(ss, 16); ss += __shfl_xor(ss, 32); if (fq == 0) rss[(size_t)row * 16 + u.pn * 4 + wc] = ss; }
.LBB0_549:
	s_and_b64 vcc, exec, s[12:13]
	s_cbranch_vccnz .LBB0_553
	v_mul_f32_e32 v135, v135, v135
	v_fmac_f32_e32 v135, v134, v134
	v_mul_f32_e32 v134, v137, v137
	v_fmac_f32_e32 v134, v136, v136
	v_add_f32_e32 v134, v135, v134
	v_mul_f32_e32 v135, v139, v139
	v_fmac_f32_e32 v135, v138, v138
	v_mul_f32_e32 v131, v131, v131
	v_add_f32_e32 v134, v135, v134
	v_mul_f32_e32 v135, v141, v141
	v_fmac_f32_e32 v131, v130, v130
	v_mul_f32_e32 v130, v133, v133
	v_fmac_f32_e32 v135, v140, v140
	v_mul_f32_e32 v136, v143, v143
	v_fmac_f32_e32 v130, v132, v132
	v_add_f32_e32 v134, v135, v134
	v_mul_f32_e32 v135, v145, v145
	v_fmac_f32_e32 v136, v142, v142
	v_add_f32_e32 v130, v131, v130
	v_fmac_f32_e32 v135, v144, v144
	v_add_f32_e32 v130, v136, v130
	v_add_f32_e32 v130, v135, v130
	v_add_f32_e32 v130, v134, v130
	v_mov_b32_e32 v131, v130
	s_nop 1
	v_permlane16_swap_b32_e32 v131, v130
	s_waitcnt lgkmcnt(0)
	v_add_f32_e32 v130, v130, v131
	s_nop 1
	v_mov_b32_e32 v131, v130
	s_nop 1
	v_permlane32_swap_b32_e32 v131, v130
	s_and_saveexec_b64 s[10:11], s[4:5]
	s_cbranch_execz .LBB0_552
	v_readlane_b32 s12, v255, 5
	s_waitcnt lgkmcnt(0)
	v_add_f32_e32 v132, v130, v131
	v_lshlrev_b64 v[130:131], 6, v[218:219]
	v_readlane_b32 s13, v255, 6
	s_lshl_b32 s46, s43, 2
	s_nop 0
	v_lshl_add_u64 v[130:131], s[12:13], 0, v[130:131]
	v_lshl_add_u64 v[130:131], s[82:83], 2, v[130:131]
	v_lshl_add_u64 v[130:131], v[130:131], 0, s[46:47]
	global_store_dword v[130:131], v132, off

;     DI void operator()(const f32x4 (&acc)[2][2][4][2], const Unit& u, int wr, int wc, int fr, int fq) const {
;     ...
;                     ss += (x0[0] * x0[0] + x0[1] * x0[1]) + (x0[2] * x0[2] + x0[3] * x0[3]) + (x1[0] * x1[0] + x1[1] * x1[1]) + (x1[2] * x1[2] + x1[3] * x1[3]);
;                 }
;                 if (rss) { ss += __shfl_xor(ss, 16); ss += __shfl_xor(ss, 32); if (fq == 0) rss[(size_t)row * 16 + u.pn * 4 + wc] = ss; }
.LBB0_562:
	s_lshl_b32 s82, s95, 2
	v_cndmask_b32_e64 v130, 0, 1, s[52:53]
	v_cmp_ne_u32_e64 s[12:13], 1, v130
	s_andn2_b64 vcc, exec, s[52:53]
	s_ashr_i32 s83, s82, 31
	s_cbranch_vccnz .LBB0_566
	v_mul_f32_e32 v127, v127, v127
	v_mul_f32_e32 v117, v117, v117
	v_mul_f32_e32 v115, v115, v115
	v_fmac_f32_e32 v127, v126, v126
	v_mul_f32_e32 v126, v129, v129
	v_fmac_f32_e32 v117, v116, v116
	v_fmac_f32_e32 v115, v114, v114
	v_mul_f32_e32 v114, v119, v119
	v_mul_f32_e32 v116, v121, v121
	v_fmac_f32_e32 v126, v128, v128
	v_mul_f32_e32 v123, v123, v123
	v_fmac_f32_e32 v114, v118, v118
	v_fmac_f32_e32 v116, v120, v120
	v_add_f32_e32 v126, v127, v126
	v_fmac_f32_e32 v123, v122, v122
	v_add_f32_e32 v114, v114, v116
	v_add_f32_e32 v122, v123, v126
	v_mul_f32_e32 v123, v125, v125
	v_add_f32_e32 v114, v115, v114
	v_fmac_f32_e32 v123, v124, v124
	v_add_f32_e32 v122, v123, v122
	v_add_f32_e32 v114, v117, v114
	v_add_f32_e32 v114, v122, v114
	v_mov_b32_e32 v115, v114
	s_nop 1
	v_permlane16_swap_b32_e32 v115, v114
	s_waitcnt lgkmcnt(0)
	v_add_f32_e32 v114, v114, v115
	s_nop 1
	v_mov_b32_e32 v115, v114
	s_nop 1
	v_permlane32_swap_b32_e32 v115, v114
	s_and_saveexec_b64 vcc, s[4:5]
	s_cbranch_execz .LBB0_565
	v_readlane_b32 s26, v255, 5
	s_waitcnt lgkmcnt(0)
	v_add_f32_e32 v116, v114, v115
	v_lshlrev_b64 v[114:115], 6, v[234:235]
	v_readlane_b32 s27, v255, 6
	s_lshl_b32 s46, s43, 2
	s_nop 0
	v_lshl_add_u64 v[114:115], s[26:27], 0, v[114:115]
	v_lshl_add_u64 v[114:115], s[82:83], 2, v[114:115]
	v_lshl_add_u64 v[114:115], v[114:115], 0, s[46:47]
	global_store_dword v[114:115], v116, off

;     DI void operator()(const f32x4 (&acc)[2][2][4][2], const Unit& u, int wr, int wc, int fr, int fq) const {
;     ...
;                     ss += (x0[0] * x0[0] + x0[1] * x0[1]) + (x0[2] * x0[2] + x0[3] * x0[3]) + (x1[0] * x1[0] + x1[1] * x1[1]) + (x1[2] * x1[2] + x1[3] * x1[3]);
;                 }
;                 if (rss) { ss += __shfl_xor(ss, 16); ss += __shfl_xor(ss, 32); if (fq == 0) rss[(size_t)row * 16 + u.pn * 4 + wc] = ss; }
.LBB0_574:
	s_and_b64 vcc, exec, s[12:13]
	s_cbranch_vccnz .LBB0_578
	v_mul_f32_e32 v111, v111, v111
	v_mul_f32_e32 v101, v101, v101
	v_mul_f32_e32 v99, v99, v99
	v_fmac_f32_e32 v111, v110, v110
	v_mul_f32_e32 v110, v113, v113
	v_fmac_f32_e32 v101, v100, v100
	v_fmac_f32_e32 v99, v98, v98
	v_mul_f32_e32 v98, v103, v103
	v_mul_f32_e32 v100, v105, v105
	v_fmac_f32_e32 v110, v112, v112
	v_mul_f32_e32 v107, v107, v107
	v_fmac_f32_e32 v98, v102, v102
	v_fmac_f32_e32 v100, v104, v104
	v_add_f32_e32 v110, v111, v110
	v_fmac_f32_e32 v107, v106, v106
	v_add_f32_e32 v98, v98, v100
	v_add_f32_e32 v106, v107, v110
	v_mul_f32_e32 v107, v109, v109
	v_add_f32_e32 v98, v99, v98
	v_fmac_f32_e32 v107, v108, v108
	v_add_f32_e32 v106, v107, v106
	v_add_f32_e32 v98, v101, v98
	v_add_f32_e32 v98, v106, v98
	v_mov_b32_e32 v99, v98
	s_nop 1
	v_permlane16_swap_b32_e32 v99, v98
	s_waitcnt lgkmcnt(0)
	v_add_f32_e32 v98, v98, v99
	s_nop 1
	v_mov_b32_e32 v99, v98
	s_nop 1
	v_permlane32_swap_b32_e32 v99, v98
	s_and_saveexec_b64 vcc, s[4:5]
	s_cbranch_execz .LBB0_577
	v_readlane_b32 s26, v255, 5
	s_waitcnt lgkmcnt(0)
	v_add_f32_e32 v100, v98, v99
	v_lshlrev_b64 v[98:99], 6, v[232:233]
	v_readlane_b32 s27, v255, 6
	s_lshl_b32 s46, s43, 2
	s_nop 0
	v_lshl_add_u64 v[98:99], s[26:27], 0, v[98:99]
	v_lshl_add_u64 v[98:99], s[82:83], 2, v[98:99]
	v_lshl_add_u64 v[98:99], v[98:99], 0, s[46:47]
	global_store_dword v[98:99], v100, off

;     DI void operator()(const f32x4 (&acc)[2][2][4][2], const Unit& u, int wr, int wc, int fr, int fq) const {
;     ...
;                     ss += (x0[0] * x0[0] + x0[1] * x0[1]) + (x0[2] * x0[2] + x0[3] * x0[3]) + (x1[0] * x1[0] + x1[1] * x1[1]) + (x1[2] * x1[2] + x1[3] * x1[3]);
;                 }
;                 if (rss) { ss += __shfl_xor(ss, 16); ss += __shfl_xor(ss, 32); if (fq == 0) rss[(size_t)row * 16 + u.pn * 4 + wc] = ss; }
.LBB0_586:
	s_and_b64 vcc, exec, s[12:13]
	s_cbranch_vccnz .LBB0_590
	v_mul_f32_e32 v95, v95, v95
	v_mul_f32_e32 v85, v85, v85
	v_mul_f32_e32 v83, v83, v83
	v_fmac_f32_e32 v95, v94, v94
	v_mul_f32_e32 v94, v97, v97
	v_fmac_f32_e32 v85, v84, v84
	v_fmac_f32_e32 v83, v82, v82
	v_mul_f32_e32 v82, v87, v87
	v_mul_f32_e32 v84, v89, v89
	v_fmac_f32_e32 v94, v96, v96
	v_mul_f32_e32 v91, v91, v91
	v_fmac_f32_e32 v82, v86, v86
	v_fmac_f32_e32 v84, v88, v88
	v_add_f32_e32 v94, v95, v94
	v_fmac_f32_e32 v91, v90, v90
	v_add_f32_e32 v82, v82, v84
	v_add_f32_e32 v90, v91, v94
	v_mul_f32_e32 v91, v93, v93
	v_add_f32_e32 v82, v83, v82
	v_fmac_f32_e32 v91, v92, v92
	v_add_f32_e32 v90, v91, v90
	v_add_f32_e32 v82, v85, v82
	v_add_f32_e32 v82, v90, v82
	v_mov_b32_e32 v83, v82
	s_nop 1
	v_permlane16_swap_b32_e32 v83, v82
	s_waitcnt lgkmcnt(0)
	v_add_f32_e32 v82, v82, v83
	s_nop 1
	v_mov_b32_e32 v83, v82
	s_nop 1
	v_permlane32_swap_b32_e32 v83, v82
	s_and_saveexec_b64 vcc, s[4:5]
	s_cbranch_execz .LBB0_589
	v_readlane_b32 s26, v255, 5
	s_waitcnt lgkmcnt(0)
	v_add_f32_e32 v84, v82, v83
	v_lshlrev_b64 v[82:83], 6, v[230:231]
	v_readlane_b32 s27, v255, 6
	s_lshl_b32 s46, s43, 2
	s_nop 0
	v_lshl_add_u64 v[82:83], s[26:27], 0, v[82:83]
	v_lshl_add_u64 v[82:83], s[82:83], 2, v[82:83]
	v_lshl_add_u64 v[82:83], v[82:83], 0, s[46:47]
	global_store_dword v[82:83], v84, off

;     DI void operator()(const f32x4 (&acc)[2][2][4][2], const Unit& u, int wr, int wc, int fr, int fq) const {
;     ...
;                     ss += (x0[0] * x0[0] + x0[1] * x0[1]) + (x0[2] * x0[2] + x0[3] * x0[3]) + (x1[0] * x1[0] + x1[1] * x1[1]) + (x1[2] * x1[2] + x1[3] * x1[3]);
;                 }
;                 if (rss) { ss += __shfl_xor(ss, 16); ss += __shfl_xor(ss, 32); if (fq == 0) rss[(size_t)row * 16 + u.pn * 4 + wc] = ss; }
.LBB0_598:
	s_and_b64 vcc, exec, s[12:13]
	s_cbranch_vccnz .LBB0_602
	v_mul_f32_e32 v79, v79, v79
	v_mul_f32_e32 v69, v69, v69
	v_mul_f32_e32 v67, v67, v67
	v_fmac_f32_e32 v79, v78, v78
	v_mul_f32_e32 v78, v81, v81
	v_fmac_f32_e32 v69, v68, v68
	v_fmac_f32_e32 v67, v66, v66
	v_mul_f32_e32 v66, v71, v71
	v_mul_f32_e32 v68, v73, v73
	v_fmac_f32_e32 v78, v80, v80
	v_mul_f32_e32 v75, v75, v75
	v_fmac_f32_e32 v66, v70, v70
	v_fmac_f32_e32 v68, v72, v72
	v_add_f32_e32 v78, v79, v78
	v_fmac_f32_e32 v75, v74, v74
	v_add_f32_e32 v66, v66, v68
	v_add_f32_e32 v74, v75, v78
	v_mul_f32_e32 v75, v77, v77
	v_add_f32_e32 v66, v67, v66
	v_fmac_f32_e32 v75, v76, v76
	v_add_f32_e32 v74, v75, v74
	v_add_f32_e32 v66, v69, v66
	v_add_f32_e32 v66, v74, v66
	v_mov_b32_e32 v67, v66
	s_nop 1
	v_permlane16_swap_b32_e32 v67, v66
	s_waitcnt lgkmcnt(0)
	v_add_f32_e32 v66, v66, v67
	s_nop 1
	v_mov_b32_e32 v67, v66
	s_nop 1
	v_permlane32_swap_b32_e32 v67, v66
	s_and_saveexec_b64 vcc, s[4:5]
	s_cbranch_execz .LBB0_601
	v_readlane_b32 s26, v255, 5
	s_waitcnt lgkmcnt(0)
	v_add_f32_e32 v68, v66, v67
	v_lshlrev_b64 v[66:67], 6, v[228:229]
	v_readlane_b32 s27, v255, 6
	s_lshl_b32 s46, s43, 2
	s_nop 0
	v_lshl_add_u64 v[66:67], s[26:27], 0, v[66:67]
	v_lshl_add_u64 v[66:67], s[82:83], 2, v[66:67]
	v_lshl_add_u64 v[66:67], v[66:67], 0, s[46:47]
	global_store_dword v[66:67], v68, off

;     DI void operator()(const f32x4 (&acc)[2][2][4][2], const Unit& u, int wr, int wc, int fr, int fq) const {
;     ...
;                     ss += (x0[0] * x0[0] + x0[1] * x0[1]) + (x0[2] * x0[2] + x0[3] * x0[3]) + (x1[0] * x1[0] + x1[1] * x1[1]) + (x1[2] * x1[2] + x1[3] * x1[3]);
;                 }
;                 if (rss) { ss += __shfl_xor(ss, 16); ss += __shfl_xor(ss, 32); if (fq == 0) rss[(size_t)row * 16 + u.pn * 4 + wc] = ss; }
.LBB0_610:
	s_and_b64 vcc, exec, s[12:13]
	s_cbranch_vccnz .LBB0_614
	v_mul_f32_e32 v63, v63, v63
	v_mul_f32_e32 v53, v53, v53
	v_mul_f32_e32 v51, v51, v51
	v_fmac_f32_e32 v63, v62, v62
	v_mul_f32_e32 v62, v65, v65
	v_fmac_f32_e32 v53, v52, v52
	v_fmac_f32_e32 v51, v50, v50
	v_mul_f32_e32 v50, v55, v55
	v_mul_f32_e32 v52, v57, v57
	v_fmac_f32_e32 v62, v64, v64
	v_mul_f32_e32 v59, v59, v59
	v_fmac_f32_e32 v50, v54, v54
	v_fmac_f32_e32 v52, v56, v56
	v_add_f32_e32 v62, v63, v62
	v_fmac_f32_e32 v59, v58, v58
	v_add_f32_e32 v50, v50, v52
	v_add_f32_e32 v58, v59, v62
	v_mul_f32_e32 v59, v61, v61
	v_add_f32_e32 v50, v51, v50
	v_fmac_f32_e32 v59, v60, v60
	v_add_f32_e32 v58, v59, v58
	v_add_f32_e32 v50, v53, v50
	v_add_f32_e32 v50, v58, v50
	v_mov_b32_e32 v51, v50
	s_nop 1
	v_permlane16_swap_b32_e32 v51, v50
	s_waitcnt lgkmcnt(0)
	v_add_f32_e32 v50, v50, v51
	s_nop 1
	v_mov_b32_e32 v51, v50
	s_nop 1
	v_permlane32_swap_b32_e32 v51, v50
	s_and_saveexec_b64 vcc, s[4:5]
	s_cbranch_execz .LBB0_613
	v_readlane_b32 s26, v255, 5
	s_waitcnt lgkmcnt(0)
	v_add_f32_e32 v52, v50, v51
	v_lshlrev_b64 v[50:51], 6, v[226:227]
	v_readlane_b32 s27, v255, 6
	s_lshl_b32 s46, s43, 2
	s_nop 0
	v_lshl_add_u64 v[50:51], s[26:27], 0, v[50:51]
	v_lshl_add_u64 v[50:51], s[82:83], 2, v[50:51]
	v_lshl_add_u64 v[50:51], v[50:51], 0, s[46:47]
	global_store_dword v[50:51], v52, off

;     DI void operator()(const f32x4 (&acc)[2][2][4][2], const Unit& u, int wr, int wc, int fr, int fq) const {
;     ...
;                     ss += (x0[0] * x0[0] + x0[1] * x0[1]) + (x0[2] * x0[2] + x0[3] * x0[3]) + (x1[0] * x1[0] + x1[1] * x1[1]) + (x1[2] * x1[2] + x1[3] * x1[3]);
;                 }
;                 if (rss) { ss += __shfl_xor(ss, 16); ss += __shfl_xor(ss, 32); if (fq == 0) rss[(size_t)row * 16 + u.pn * 4 + wc] = ss; }
.LBB0_622:
	s_and_b64 vcc, exec, s[12:13]
	s_cbranch_vccnz .LBB0_626
	v_mul_f32_e32 v47, v47, v47
	v_mul_f32_e32 v37, v37, v37
	v_mul_f32_e32 v35, v35, v35
	v_fmac_f32_e32 v47, v46, v46
	v_mul_f32_e32 v46, v49, v49
	v_fmac_f32_e32 v37, v36, v36
	v_fmac_f32_e32 v35, v34, v34
	v_mul_f32_e32 v34, v39, v39
	v_mul_f32_e32 v36, v41, v41
	v_fmac_f32_e32 v46, v48, v48
	v_mul_f32_e32 v43, v43, v43
	v_fmac_f32_e32 v34, v38, v38
	v_fmac_f32_e32 v36, v40, v40
	v_add_f32_e32 v46, v47, v46
	v_fmac_f32_e32 v43, v42, v42
	v_add_f32_e32 v34, v34, v36
	v_add_f32_e32 v42, v43, v46
	v_mul_f32_e32 v43, v45, v45
	v_add_f32_e32 v34, v35, v34
	v_fmac_f32_e32 v43, v44, v44
	v_add_f32_e32 v42, v43, v42
	v_add_f32_e32 v34, v37, v34
	v_add_f32_e32 v34, v42, v34
	v_mov_b32_e32 v35, v34
	s_nop 1
	v_permlane16_swap_b32_e32 v35, v34
	s_waitcnt lgkmcnt(0)
	v_add_f32_e32 v34, v34, v35
	s_nop 1
	v_mov_b32_e32 v35, v34
	s_nop 1
	v_permlane32_swap_b32_e32 v35, v34
	s_and_saveexec_b64 vcc, s[4:5]
	s_cbranch_execz .LBB0_625
	v_readlane_b32 s26, v255, 5
	s_waitcnt lgkmcnt(0)
	v_add_f32_e32 v36, v34, v35
	v_lshlrev_b64 v[34:35], 6, v[224:225]
	v_readlane_b32 s27, v255, 6
	s_lshl_b32 s46, s43, 2
	s_nop 0
	v_lshl_add_u64 v[34:35], s[26:27], 0, v[34:35]
	v_lshl_add_u64 v[34:35], s[82:83], 2, v[34:35]
	v_lshl_add_u64 v[34:35], v[34:35], 0, s[46:47]
	global_store_dword v[34:35], v36, off

;     DI void operator()(const f32x4 (&acc)[2][2][4][2], const Unit& u, int wr, int wc, int fr, int fq) const {
;     ...
;                     ss += (x0[0] * x0[0] + x0[1] * x0[1]) + (x0[2] * x0[2] + x0[3] * x0[3]) + (x1[0] * x1[0] + x1[1] * x1[1]) + (x1[2] * x1[2] + x1[3] * x1[3]);
;                 }
;                 if (rss) { ss += __shfl_xor(ss, 16); ss += __shfl_xor(ss, 32); if (fq == 0) rss[(size_t)row * 16 + u.pn * 4 + wc] = ss; }
.LBB0_634:
	s_and_b64 vcc, exec, s[12:13]
	s_cbranch_vccnz .LBB0_638
	v_mul_f32_e32 v31, v31, v31
	v_mul_f32_e32 v21, v21, v21
	v_mul_f32_e32 v19, v19, v19
	v_fmac_f32_e32 v31, v30, v30
	v_mul_f32_e32 v30, v33, v33
	v_fmac_f32_e32 v21, v20, v20
	v_fmac_f32_e32 v19, v18, v18
	v_mul_f32_e32 v18, v23, v23
	v_mul_f32_e32 v20, v25, v25
	v_fmac_f32_e32 v30, v32, v32
	v_mul_f32_e32 v27, v27, v27
	v_fmac_f32_e32 v18, v22, v22
	v_fmac_f32_e32 v20, v24, v24
	v_add_f32_e32 v30, v31, v30
	v_fmac_f32_e32 v27, v26, v26
	v_add_f32_e32 v18, v18, v20
	v_add_f32_e32 v26, v27, v30
	v_mul_f32_e32 v27, v29, v29
	v_add_f32_e32 v18, v19, v18
	v_fmac_f32_e32 v27, v28, v28
	v_add_f32_e32 v26, v27, v26
	v_add_f32_e32 v18, v21, v18
	v_add_f32_e32 v18, v26, v18
	v_mov_b32_e32 v19, v18
	s_nop 1
	v_permlane16_swap_b32_e32 v19, v18
	s_waitcnt lgkmcnt(0)
	v_add_f32_e32 v18, v18, v19
	s_nop 1
	v_mov_b32_e32 v19, v18
	s_nop 1
	v_permlane32_swap_b32_e32 v19, v18
	s_and_saveexec_b64 vcc, s[4:5]
	s_cbranch_execz .LBB0_637
	v_readlane_b32 s26, v255, 5
	s_waitcnt lgkmcnt(0)
	v_add_f32_e32 v20, v18, v19
	v_lshlrev_b64 v[18:19], 6, v[222:223]
	v_readlane_b32 s27, v255, 6
	s_lshl_b32 s46, s43, 2
	s_nop 0
	v_lshl_add_u64 v[18:19], s[26:27], 0, v[18:19]
	v_lshl_add_u64 v[18:19], s[82:83], 2, v[18:19]
	v_lshl_add_u64 v[18:19], v[18:19], 0, s[46:47]
	global_store_dword v[18:19], v20, off

;     DI void operator()(const f32x4 (&acc)[2][2][4][2], const Unit& u, int wr, int wc, int fr, int fq) const {
;     ...
;                     ss += (x0[0] * x0[0] + x0[1] * x0[1]) + (x0[2] * x0[2] + x0[3] * x0[3]) + (x1[0] * x1[0] + x1[1] * x1[1]) + (x1[2] * x1[2] + x1[3] * x1[3]);
;                 }
;                 if (rss) { ss += __shfl_xor(ss, 16); ss += __shfl_xor(ss, 32); if (fq == 0) rss[(size_t)row * 16 + u.pn * 4 + wc] = ss; }
.LBB0_646:
	s_and_b64 vcc, exec, s[12:13]
	s_cbranch_vccnz .LBB0_650
	v_mul_f32_e32 v15, v15, v15
	v_mul_f32_e32 v5, v5, v5
	v_mul_f32_e32 v3, v3, v3
	v_fmac_f32_e32 v15, v14, v14
	v_mul_f32_e32 v14, v17, v17
	v_fmac_f32_e32 v5, v4, v4
	v_fmac_f32_e32 v3, v2, v2
	v_mul_f32_e32 v2, v7, v7
	v_mul_f32_e32 v4, v9, v9
	v_fmac_f32_e32 v14, v16, v16
	v_mul_f32_e32 v11, v11, v11
	v_fmac_f32_e32 v2, v6, v6
	v_fmac_f32_e32 v4, v8, v8
	v_add_f32_e32 v14, v15, v14
	v_fmac_f32_e32 v11, v10, v10
	v_add_f32_e32 v2, v2, v4
	v_add_f32_e32 v10, v11, v14
	v_mul_f32_e32 v11, v13, v13
	v_add_f32_e32 v2, v3, v2
	v_fmac_f32_e32 v11, v12, v12
	v_add_f32_e32 v10, v11, v10
	v_add_f32_e32 v2, v5, v2
	v_add_f32_e32 v2, v10, v2
	v_mov_b32_e32 v3, v2
	s_nop 1
	v_permlane16_swap_b32_e32 v3, v2
	s_waitcnt lgkmcnt(0)
	v_add_f32_e32 v2, v2, v3
	s_nop 1
	v_mov_b32_e32 v3, v2
	s_nop 1
	v_permlane32_swap_b32_e32 v3, v2
	s_and_saveexec_b64 s[8:9], s[4:5]
	s_cbranch_execz .LBB0_649
	v_readlane_b32 s10, v255, 5
	s_waitcnt lgkmcnt(0)
	v_add_f32_e32 v4, v2, v3
	v_lshlrev_b64 v[2:3], 6, v[218:219]
	v_readlane_b32 s11, v255, 6
	s_lshl_b32 s46, s43, 2
	s_nop 0
	v_lshl_add_u64 v[2:3], s[10:11], 0, v[2:3]
	v_lshl_add_u64 v[2:3], s[82:83], 2, v[2:3]
	v_lshl_add_u64 v[2:3], v[2:3], 0, s[46:47]
	global_store_dword v[2:3], v4, off
